# SSM phase: one static s_setprio 1 for the context-scan waves (4-7) instead, reset at the end of the phase
# baseline (speedup 1.0000x reference)
.Lssm_ctx:
	s_setprio 1
	s_mov_b32 s27, 0
